# v60 + residual-add epilogue: the 16 bf16 activation-copy stores buffered in spare VGPRs and issued last, after all f32 residual stores (L2 recency for the next phase's A operand)
# speedup vs baseline: 1.0099x; 1.0099x over previous
.LBB0_234:
	s_lshl_b32 s29, s54, 8
	v_mov_b32_e32 v140, v144
	v_mov_b32_e32 v166, v145
	s_add_i32 s29, s29, s62
	v_readlane_b32 s50, v235, 13
	v_add_u32_e32 v142, s29, v140
	s_lshl_b32 s29, s28, 8
	s_or_b32 s29, s29, s63
	v_lshl_add_u32 v140, v166, 3, s29
	v_ashrrev_i32_e32 v143, 31, v142
	v_ashrrev_i32_e32 v141, 31, v140
	v_lshlrev_b64 v[148:149], 10, v[142:143]
	v_lshl_add_u64 v[156:157], v[148:149], 0, v[140:141]
	v_lshlrev_b64 v[158:159], 2, v[156:157]
	v_readlane_b32 s51, v235, 14
	v_lshl_add_u64 v[162:163], v[156:157], 1, s[22:23]
	v_lshl_add_u64 v[164:165], s[70:71], 0, v[158:159]
	v_lshl_add_u64 v[160:161], s[50:51], 0, v[158:159]
	global_load_dwordx4 v[148:151], v[160:161], off
	global_load_dwordx4 v[152:155], v[160:161], off offset:16
	s_lshl_b32 s54, s28, 2
	s_ashr_i32 s55, s54, 31
	s_waitcnt vmcnt(0)
	v_pk_add_f32 v[150:151], v[124:125], v[150:151]
	v_pk_add_f32 v[148:149], v[122:123], v[148:149]
	v_pk_add_f32 v[128:129], v[128:129], v[154:155]
	v_pk_add_f32 v[126:127], v[126:127], v[152:153]
	v_cvt_pk_bf16_f32 v122, v148, v149
	v_cvt_pk_bf16_f32 v123, v150, v151
	v_cvt_pk_bf16_f32 v124, v126, v127
	v_cvt_pk_bf16_f32 v125, v128, v129
	global_store_dwordx4 v[164:165], v[148:151], off
	global_store_dwordx4 v[164:165], v[126:129], off offset:16
	v_mov_b64_e32 v[200:201], v[122:123]
	v_mov_b64_e32 v[202:203], v[124:125]
	v_subrev_u32_e32 v188, s22, v162
	global_load_dwordx4 v[152:155], v[160:161], off offset:512
	global_load_dwordx4 v[156:159], v[160:161], off offset:528
	v_and_b32_e32 v123, 64, v192
	v_xor_b32_e32 v122, 16, v192
	v_add_u32_e32 v123, 64, v123
	v_xor_b32_e32 v124, 32, v192
	v_cmp_lt_i32_e32 vcc, v122, v123
	v_mul_f32_e32 v125, v151, v151
	v_mul_f32_e32 v127, v127, v127
	v_cndmask_b32_e32 v122, v192, v122, vcc
	v_cmp_lt_i32_e32 vcc, v124, v123
	v_lshlrev_b32_e32 v123, 2, v122
	v_mul_f32_e32 v129, v129, v129
	v_cndmask_b32_e32 v124, v192, v124, vcc
	v_lshlrev_b32_e32 v122, 2, v124
	v_mul_f32_e32 v124, v149, v149
	v_fmac_f32_e32 v124, v148, v148
	v_fmac_f32_e32 v125, v150, v150
	v_fmac_f32_e32 v127, v126, v126
	v_fmac_f32_e32 v129, v128, v128
	v_add_f32_e32 v124, v124, v125
	v_add_f32_e32 v125, v127, v129
	v_add_f32_e32 v128, v125, v124
	v_cmp_eq_u32_e32 vcc, 0, v166
	s_waitcnt vmcnt(0)
	v_pk_add_f32 v[120:121], v[120:121], v[154:155]
	v_pk_add_f32 v[118:119], v[118:119], v[152:153]
	v_pk_add_f32 v[126:127], v[116:117], v[158:159]
	v_pk_add_f32 v[124:125], v[114:115], v[156:157]
	v_mul_f32_e32 v114, v119, v119
	v_mul_f32_e32 v115, v121, v121
	v_mul_f32_e32 v116, v125, v125
	v_mul_f32_e32 v117, v127, v127
	v_fmac_f32_e32 v114, v118, v118
	v_fmac_f32_e32 v115, v120, v120
	v_fmac_f32_e32 v116, v124, v124
	v_fmac_f32_e32 v117, v126, v126
	v_add_f32_e32 v114, v114, v115
	v_add_f32_e32 v115, v116, v117
	v_add_f32_e32 v114, v115, v114
	v_add_f32_e32 v114, v128, v114
	ds_bpermute_b32 v115, v123, v114
	global_store_dwordx4 v[164:165], v[118:121], off offset:512
	global_store_dwordx4 v[164:165], v[124:127], off offset:528
	v_cvt_pk_bf16_f32 v116, v118, v119
	v_cvt_pk_bf16_f32 v117, v120, v121
	v_cvt_pk_bf16_f32 v118, v124, v125
	s_waitcnt lgkmcnt(0)
	v_add_f32_e32 v114, v114, v115
	ds_bpermute_b32 v115, v122, v114
	v_cvt_pk_bf16_f32 v119, v126, v127
	v_mov_b64_e32 v[204:205], v[116:117]
	v_mov_b64_e32 v[206:207], v[118:119]
	s_and_saveexec_b64 s[50:51], vcc
	s_cbranch_execz .LBB0_236
	v_readlane_b32 s28, v235, 1
	v_lshlrev_b64 v[116:117], 6, v[142:143]
	v_readlane_b32 s29, v235, 2
	s_lshl_b32 s78, s60, 2
	s_waitcnt lgkmcnt(0)
	v_add_f32_e32 v114, v114, v115
	v_lshl_add_u64 v[116:117], s[28:29], 0, v[116:117]
	v_lshl_add_u64 v[116:117], s[54:55], 2, v[116:117]
	v_lshl_add_u64 v[116:117], v[116:117], 0, s[78:79]
	s_mov_b32 s78, s76
	global_store_dword v[116:117], v114, off
.LBB0_236:
	s_or_b64 exec, exec, s[50:51]
	v_add_u32_e32 v114, 16, v142
	s_waitcnt lgkmcnt(0)
	v_ashrrev_i32_e32 v115, 31, v114
	v_lshlrev_b64 v[116:117], 10, v[114:115]
	v_lshl_add_u64 v[120:121], v[116:117], 0, v[140:141]
	v_readlane_b32 s28, v235, 13
	v_lshlrev_b64 v[128:129], 2, v[120:121]
	v_readlane_b32 s29, v235, 14
	v_lshl_add_u64 v[120:121], v[120:121], 1, s[22:23]
	s_nop 0
	v_lshl_add_u64 v[148:149], s[28:29], 0, v[128:129]
	global_load_dwordx4 v[116:119], v[148:149], off
	global_load_dwordx4 v[124:127], v[148:149], off offset:16
	v_lshl_add_u64 v[128:129], s[70:71], 0, v[128:129]
	s_waitcnt vmcnt(1)
	v_pk_add_f32 v[112:113], v[112:113], v[118:119]
	v_pk_add_f32 v[110:111], v[110:111], v[116:117]
	s_waitcnt vmcnt(0)
	v_pk_add_f32 v[108:109], v[108:109], v[126:127]
	v_pk_add_f32 v[106:107], v[106:107], v[124:125]
	v_cvt_pk_bf16_f32 v116, v110, v111
	v_cvt_pk_bf16_f32 v117, v112, v113
	v_cvt_pk_bf16_f32 v118, v106, v107
	v_cvt_pk_bf16_f32 v119, v108, v109
	global_store_dwordx4 v[128:129], v[110:113], off
	global_store_dwordx4 v[128:129], v[106:109], off offset:16
	v_mov_b64_e32 v[208:209], v[116:117]
	v_mov_b64_e32 v[210:211], v[118:119]
	v_subrev_u32_e32 v189, s22, v120
	global_load_dwordx4 v[116:119], v[148:149], off offset:512
	s_nop 0
	global_load_dwordx4 v[124:127], v[148:149], off offset:528
	v_mul_f32_e32 v111, v111, v111
	v_mul_f32_e32 v113, v113, v113
	v_mul_f32_e32 v107, v107, v107
	v_mul_f32_e32 v109, v109, v109
	v_fmac_f32_e32 v111, v110, v110
	v_fmac_f32_e32 v113, v112, v112
	v_fmac_f32_e32 v107, v106, v106
	v_fmac_f32_e32 v109, v108, v108
	v_add_f32_e32 v106, v111, v113
	v_add_f32_e32 v107, v107, v109
	v_add_f32_e32 v110, v107, v106
	s_waitcnt vmcnt(1)
	v_pk_add_f32 v[104:105], v[104:105], v[118:119]
	v_pk_add_f32 v[102:103], v[102:103], v[116:117]
	s_waitcnt vmcnt(0)
	v_pk_add_f32 v[108:109], v[100:101], v[126:127]
	v_pk_add_f32 v[106:107], v[98:99], v[124:125]
	v_mul_f32_e32 v98, v103, v103
	v_mul_f32_e32 v99, v105, v105
	v_mul_f32_e32 v100, v107, v107
	v_mul_f32_e32 v101, v109, v109
	v_fmac_f32_e32 v98, v102, v102
	v_fmac_f32_e32 v99, v104, v104
	v_fmac_f32_e32 v100, v106, v106
	v_fmac_f32_e32 v101, v108, v108
	v_add_f32_e32 v98, v98, v99
	v_add_f32_e32 v99, v100, v101
	v_add_f32_e32 v98, v99, v98
	v_add_f32_e32 v98, v110, v98
	ds_bpermute_b32 v99, v123, v98
	global_store_dwordx4 v[128:129], v[102:105], off offset:512
	global_store_dwordx4 v[128:129], v[106:109], off offset:528
	v_cvt_pk_bf16_f32 v100, v102, v103
	v_cvt_pk_bf16_f32 v101, v104, v105
	v_cvt_pk_bf16_f32 v102, v106, v107
	s_waitcnt lgkmcnt(0)
	v_add_f32_e32 v98, v98, v99
	ds_bpermute_b32 v99, v122, v98
	v_cvt_pk_bf16_f32 v103, v108, v109
	v_mov_b64_e32 v[212:213], v[100:101]
	v_mov_b64_e32 v[214:215], v[102:103]
	s_and_saveexec_b64 s[50:51], vcc
	s_cbranch_execz .LBB0_238
	v_readlane_b32 s28, v235, 1
	v_lshlrev_b64 v[100:101], 6, v[114:115]
	v_readlane_b32 s29, v235, 2
	s_lshl_b32 s78, s60, 2
	s_waitcnt lgkmcnt(0)
	v_add_f32_e32 v98, v98, v99
	v_lshl_add_u64 v[100:101], s[28:29], 0, v[100:101]
	v_lshl_add_u64 v[100:101], s[54:55], 2, v[100:101]
	v_lshl_add_u64 v[100:101], v[100:101], 0, s[78:79]
	s_mov_b32 s78, s76
	global_store_dword v[100:101], v98, off
.LBB0_238:
	s_or_b64 exec, exec, s[50:51]
	v_add_u32_e32 v98, 32, v142
	s_waitcnt lgkmcnt(0)
	v_ashrrev_i32_e32 v99, 31, v98
	v_lshlrev_b64 v[100:101], 10, v[98:99]
	v_lshl_add_u64 v[108:109], v[100:101], 0, v[140:141]
	v_readlane_b32 s28, v235, 13
	v_lshlrev_b64 v[110:111], 2, v[108:109]
	v_readlane_b32 s29, v235, 14
	v_lshl_add_u64 v[108:109], v[108:109], 1, s[22:23]
	s_nop 0
	v_lshl_add_u64 v[112:113], s[28:29], 0, v[110:111]
	global_load_dwordx4 v[100:103], v[112:113], off
	global_load_dwordx4 v[104:107], v[112:113], off offset:16
	v_lshl_add_u64 v[110:111], s[70:71], 0, v[110:111]
	s_waitcnt vmcnt(1)
	v_pk_add_f32 v[96:97], v[96:97], v[102:103]
	v_pk_add_f32 v[94:95], v[94:95], v[100:101]
	s_waitcnt vmcnt(0)
	v_pk_add_f32 v[92:93], v[92:93], v[106:107]
	v_pk_add_f32 v[90:91], v[90:91], v[104:105]
	v_cvt_pk_bf16_f32 v100, v94, v95
	v_cvt_pk_bf16_f32 v101, v96, v97
	v_cvt_pk_bf16_f32 v102, v90, v91
	v_cvt_pk_bf16_f32 v103, v92, v93
	global_store_dwordx4 v[110:111], v[94:97], off
	global_store_dwordx4 v[110:111], v[90:93], off offset:16
	v_mov_b64_e32 v[216:217], v[100:101]
	v_mov_b64_e32 v[218:219], v[102:103]
	v_subrev_u32_e32 v167, s22, v108
	global_load_dwordx4 v[100:103], v[112:113], off offset:512
	s_nop 0
	global_load_dwordx4 v[104:107], v[112:113], off offset:528
	v_mul_f32_e32 v95, v95, v95
	v_mul_f32_e32 v97, v97, v97
	v_mul_f32_e32 v91, v91, v91
	v_mul_f32_e32 v93, v93, v93
	v_fmac_f32_e32 v95, v94, v94
	v_fmac_f32_e32 v97, v96, v96
	v_fmac_f32_e32 v91, v90, v90
	v_fmac_f32_e32 v93, v92, v92
	v_add_f32_e32 v90, v95, v97
	v_add_f32_e32 v91, v91, v93
	v_add_f32_e32 v94, v91, v90
	s_waitcnt vmcnt(1)
	v_pk_add_f32 v[88:89], v[88:89], v[102:103]
	v_pk_add_f32 v[86:87], v[86:87], v[100:101]
	s_waitcnt vmcnt(0)
	v_pk_add_f32 v[92:93], v[84:85], v[106:107]
	v_pk_add_f32 v[90:91], v[82:83], v[104:105]
	v_mul_f32_e32 v82, v87, v87
	v_mul_f32_e32 v83, v89, v89
	v_mul_f32_e32 v84, v91, v91
	v_mul_f32_e32 v85, v93, v93
	v_fmac_f32_e32 v82, v86, v86
	v_fmac_f32_e32 v83, v88, v88
	v_fmac_f32_e32 v84, v90, v90
	v_fmac_f32_e32 v85, v92, v92
	v_add_f32_e32 v82, v82, v83
	v_add_f32_e32 v83, v84, v85
	v_add_f32_e32 v82, v83, v82
	v_add_f32_e32 v82, v94, v82
	ds_bpermute_b32 v83, v123, v82
	global_store_dwordx4 v[110:111], v[86:89], off offset:512
	global_store_dwordx4 v[110:111], v[90:93], off offset:528
	v_cvt_pk_bf16_f32 v84, v86, v87
	v_cvt_pk_bf16_f32 v85, v88, v89
	v_cvt_pk_bf16_f32 v86, v90, v91
	s_waitcnt lgkmcnt(0)
	v_add_f32_e32 v82, v82, v83
	ds_bpermute_b32 v83, v122, v82
	v_cvt_pk_bf16_f32 v87, v92, v93
	v_mov_b64_e32 v[220:221], v[84:85]
	v_mov_b64_e32 v[222:223], v[86:87]
	s_and_saveexec_b64 s[50:51], vcc
	s_cbranch_execz .LBB0_240
	v_readlane_b32 s28, v235, 1
	v_lshlrev_b64 v[84:85], 6, v[98:99]
	v_readlane_b32 s29, v235, 2
	s_lshl_b32 s78, s60, 2
	s_waitcnt lgkmcnt(0)
	v_add_f32_e32 v82, v82, v83
	v_lshl_add_u64 v[84:85], s[28:29], 0, v[84:85]
	v_lshl_add_u64 v[84:85], s[54:55], 2, v[84:85]
	v_lshl_add_u64 v[84:85], v[84:85], 0, s[78:79]
	s_mov_b32 s78, s76
	global_store_dword v[84:85], v82, off
.LBB0_240:
	s_or_b64 exec, exec, s[50:51]
	v_add_u32_e32 v82, 48, v142
	s_waitcnt lgkmcnt(0)
	v_ashrrev_i32_e32 v83, 31, v82
	v_lshlrev_b64 v[84:85], 10, v[82:83]
	v_lshl_add_u64 v[92:93], v[84:85], 0, v[140:141]
	v_readlane_b32 s28, v235, 13
	v_lshlrev_b64 v[94:95], 2, v[92:93]
	v_readlane_b32 s29, v235, 14
	v_lshl_add_u64 v[92:93], v[92:93], 1, s[22:23]
	s_nop 0
	v_lshl_add_u64 v[96:97], s[28:29], 0, v[94:95]
	global_load_dwordx4 v[84:87], v[96:97], off
	global_load_dwordx4 v[88:91], v[96:97], off offset:16
	v_lshl_add_u64 v[94:95], s[70:71], 0, v[94:95]
	s_waitcnt vmcnt(1)
	v_pk_add_f32 v[80:81], v[80:81], v[86:87]
	v_pk_add_f32 v[78:79], v[78:79], v[84:85]
	s_waitcnt vmcnt(0)
	v_pk_add_f32 v[76:77], v[76:77], v[90:91]
	v_pk_add_f32 v[74:75], v[74:75], v[88:89]
	v_cvt_pk_bf16_f32 v84, v78, v79
	v_cvt_pk_bf16_f32 v85, v80, v81
	v_cvt_pk_bf16_f32 v86, v74, v75
	v_cvt_pk_bf16_f32 v87, v76, v77
	global_store_dwordx4 v[94:95], v[78:81], off
	global_store_dwordx4 v[94:95], v[74:77], off offset:16
	v_mov_b64_e32 v[224:225], v[84:85]
	v_mov_b64_e32 v[226:227], v[86:87]
	v_subrev_u32_e32 v238, s22, v92
	global_load_dwordx4 v[84:87], v[96:97], off offset:512
	s_nop 0
	global_load_dwordx4 v[88:91], v[96:97], off offset:528
	v_mul_f32_e32 v79, v79, v79
	v_mul_f32_e32 v81, v81, v81
	v_mul_f32_e32 v75, v75, v75
	v_mul_f32_e32 v77, v77, v77
	v_fmac_f32_e32 v79, v78, v78
	v_fmac_f32_e32 v81, v80, v80
	v_fmac_f32_e32 v75, v74, v74
	v_fmac_f32_e32 v77, v76, v76
	v_add_f32_e32 v74, v79, v81
	v_add_f32_e32 v75, v75, v77
	v_add_f32_e32 v78, v75, v74
	s_waitcnt vmcnt(1)
	v_pk_add_f32 v[72:73], v[72:73], v[86:87]
	v_pk_add_f32 v[70:71], v[70:71], v[84:85]
	s_waitcnt vmcnt(0)
	v_pk_add_f32 v[76:77], v[68:69], v[90:91]
	v_pk_add_f32 v[74:75], v[66:67], v[88:89]
	v_mul_f32_e32 v66, v71, v71
	v_mul_f32_e32 v67, v73, v73
	v_mul_f32_e32 v68, v75, v75
	v_mul_f32_e32 v69, v77, v77
	v_fmac_f32_e32 v66, v70, v70
	v_fmac_f32_e32 v67, v72, v72
	v_fmac_f32_e32 v68, v74, v74
	v_fmac_f32_e32 v69, v76, v76
	v_add_f32_e32 v66, v66, v67
	v_add_f32_e32 v67, v68, v69
	v_add_f32_e32 v66, v67, v66
	v_add_f32_e32 v66, v78, v66
	ds_bpermute_b32 v67, v123, v66
	global_store_dwordx4 v[94:95], v[70:73], off offset:512
	global_store_dwordx4 v[94:95], v[74:77], off offset:528
	v_cvt_pk_bf16_f32 v68, v70, v71
	v_cvt_pk_bf16_f32 v69, v72, v73
	v_cvt_pk_bf16_f32 v70, v74, v75
	s_waitcnt lgkmcnt(0)
	v_add_f32_e32 v66, v66, v67
	ds_bpermute_b32 v67, v122, v66
	v_cvt_pk_bf16_f32 v71, v76, v77
	v_mov_b64_e32 v[228:229], v[68:69]
	v_mov_b64_e32 v[230:231], v[70:71]
	s_and_saveexec_b64 s[50:51], vcc
	s_cbranch_execz .LBB0_242
	v_readlane_b32 s28, v235, 1
	v_lshlrev_b64 v[68:69], 6, v[82:83]
	v_readlane_b32 s29, v235, 2
	s_lshl_b32 s78, s60, 2
	s_waitcnt lgkmcnt(0)
	v_add_f32_e32 v66, v66, v67
	v_lshl_add_u64 v[68:69], s[28:29], 0, v[68:69]
	v_lshl_add_u64 v[68:69], s[54:55], 2, v[68:69]
	v_lshl_add_u64 v[68:69], v[68:69], 0, s[78:79]
	s_mov_b32 s78, s76
	global_store_dword v[68:69], v66, off
.LBB0_242:
	s_or_b64 exec, exec, s[50:51]
	v_add_u32_e32 v66, 0x80, v142
	s_waitcnt lgkmcnt(0)
	v_ashrrev_i32_e32 v67, 31, v66
	v_lshlrev_b64 v[68:69], 10, v[66:67]
	v_lshl_add_u64 v[76:77], v[68:69], 0, v[140:141]
	v_readlane_b32 s28, v235, 13
	v_lshlrev_b64 v[78:79], 2, v[76:77]
	v_readlane_b32 s29, v235, 14
	v_lshl_add_u64 v[76:77], v[76:77], 1, s[22:23]
	s_nop 0
	v_lshl_add_u64 v[80:81], s[28:29], 0, v[78:79]
	global_load_dwordx4 v[68:71], v[80:81], off
	global_load_dwordx4 v[72:75], v[80:81], off offset:16
	v_lshl_add_u64 v[78:79], s[70:71], 0, v[78:79]
	s_waitcnt vmcnt(1)
	v_pk_add_f32 v[64:65], v[64:65], v[70:71]
	v_pk_add_f32 v[62:63], v[62:63], v[68:69]
	s_waitcnt vmcnt(0)
	v_pk_add_f32 v[60:61], v[60:61], v[74:75]
	v_pk_add_f32 v[58:59], v[58:59], v[72:73]
	v_cvt_pk_bf16_f32 v68, v62, v63
	v_cvt_pk_bf16_f32 v69, v64, v65
	v_cvt_pk_bf16_f32 v70, v58, v59
	v_cvt_pk_bf16_f32 v71, v60, v61
	global_store_dwordx4 v[78:79], v[62:65], off
	global_store_dwordx4 v[78:79], v[58:61], off offset:16
	v_mov_b64_e32 v[168:169], v[68:69]
	v_mov_b64_e32 v[170:171], v[70:71]
	v_subrev_u32_e32 v239, s22, v76
	global_load_dwordx4 v[68:71], v[80:81], off offset:512
	s_nop 0
	global_load_dwordx4 v[72:75], v[80:81], off offset:528
	v_mul_f32_e32 v63, v63, v63
	v_mul_f32_e32 v65, v65, v65
	v_mul_f32_e32 v59, v59, v59
	v_mul_f32_e32 v61, v61, v61
	v_fmac_f32_e32 v63, v62, v62
	v_fmac_f32_e32 v65, v64, v64
	v_fmac_f32_e32 v59, v58, v58
	v_fmac_f32_e32 v61, v60, v60
	v_add_f32_e32 v58, v63, v65
	v_add_f32_e32 v59, v59, v61
	v_add_f32_e32 v62, v59, v58
	s_waitcnt vmcnt(1)
	v_pk_add_f32 v[56:57], v[56:57], v[70:71]
	v_pk_add_f32 v[54:55], v[54:55], v[68:69]
	s_waitcnt vmcnt(0)
	v_pk_add_f32 v[60:61], v[52:53], v[74:75]
	v_pk_add_f32 v[58:59], v[50:51], v[72:73]
	v_mul_f32_e32 v50, v55, v55
	v_mul_f32_e32 v51, v57, v57
	v_mul_f32_e32 v52, v59, v59
	v_mul_f32_e32 v53, v61, v61
	v_fmac_f32_e32 v50, v54, v54
	v_fmac_f32_e32 v51, v56, v56
	v_fmac_f32_e32 v52, v58, v58
	v_fmac_f32_e32 v53, v60, v60
	v_add_f32_e32 v50, v50, v51
	v_add_f32_e32 v51, v52, v53
	v_add_f32_e32 v50, v51, v50
	v_add_f32_e32 v50, v62, v50
	ds_bpermute_b32 v51, v123, v50
	global_store_dwordx4 v[78:79], v[54:57], off offset:512
	global_store_dwordx4 v[78:79], v[58:61], off offset:528
	v_cvt_pk_bf16_f32 v52, v54, v55
	v_cvt_pk_bf16_f32 v53, v56, v57
	v_cvt_pk_bf16_f32 v54, v58, v59
	s_waitcnt lgkmcnt(0)
	v_add_f32_e32 v50, v50, v51
	ds_bpermute_b32 v51, v122, v50
	v_cvt_pk_bf16_f32 v55, v60, v61
	v_mov_b64_e32 v[172:173], v[52:53]
	v_mov_b64_e32 v[174:175], v[54:55]
	s_and_saveexec_b64 s[50:51], vcc
	s_cbranch_execz .LBB0_244
	v_readlane_b32 s28, v235, 1
	v_lshlrev_b64 v[52:53], 6, v[66:67]
	v_readlane_b32 s29, v235, 2
	s_lshl_b32 s78, s60, 2
	s_waitcnt lgkmcnt(0)
	v_add_f32_e32 v50, v50, v51
	v_lshl_add_u64 v[52:53], s[28:29], 0, v[52:53]
	v_lshl_add_u64 v[52:53], s[54:55], 2, v[52:53]
	v_lshl_add_u64 v[52:53], v[52:53], 0, s[78:79]
	s_mov_b32 s78, s76
	global_store_dword v[52:53], v50, off
.LBB0_244:
	s_or_b64 exec, exec, s[50:51]
	v_add_u32_e32 v50, 0x90, v142
	s_waitcnt lgkmcnt(0)
	v_ashrrev_i32_e32 v51, 31, v50
	v_lshlrev_b64 v[52:53], 10, v[50:51]
	v_lshl_add_u64 v[60:61], v[52:53], 0, v[140:141]
	v_readlane_b32 s28, v235, 13
	v_lshlrev_b64 v[62:63], 2, v[60:61]
	v_readlane_b32 s29, v235, 14
	v_lshl_add_u64 v[60:61], v[60:61], 1, s[22:23]
	s_nop 0
	v_lshl_add_u64 v[64:65], s[28:29], 0, v[62:63]
	global_load_dwordx4 v[52:55], v[64:65], off
	global_load_dwordx4 v[56:59], v[64:65], off offset:16
	v_lshl_add_u64 v[62:63], s[70:71], 0, v[62:63]
	s_waitcnt vmcnt(1)
	v_pk_add_f32 v[48:49], v[48:49], v[54:55]
	v_pk_add_f32 v[46:47], v[46:47], v[52:53]
	s_waitcnt vmcnt(0)
	v_pk_add_f32 v[44:45], v[44:45], v[58:59]
	v_pk_add_f32 v[42:43], v[42:43], v[56:57]
	v_cvt_pk_bf16_f32 v52, v46, v47
	v_cvt_pk_bf16_f32 v53, v48, v49
	v_cvt_pk_bf16_f32 v54, v42, v43
	v_cvt_pk_bf16_f32 v55, v44, v45
	global_store_dwordx4 v[62:63], v[46:49], off
	global_store_dwordx4 v[62:63], v[42:45], off offset:16
	v_mov_b64_e32 v[176:177], v[52:53]
	v_mov_b64_e32 v[178:179], v[54:55]
	v_subrev_u32_e32 v252, s22, v60
	global_load_dwordx4 v[52:55], v[64:65], off offset:512
	s_nop 0
	global_load_dwordx4 v[56:59], v[64:65], off offset:528
	v_mul_f32_e32 v47, v47, v47
	v_mul_f32_e32 v49, v49, v49
	v_mul_f32_e32 v43, v43, v43
	v_mul_f32_e32 v45, v45, v45
	v_fmac_f32_e32 v47, v46, v46
	v_fmac_f32_e32 v49, v48, v48
	v_fmac_f32_e32 v43, v42, v42
	v_fmac_f32_e32 v45, v44, v44
	v_add_f32_e32 v42, v47, v49
	v_add_f32_e32 v43, v43, v45
	v_add_f32_e32 v46, v43, v42
	s_waitcnt vmcnt(1)
	v_pk_add_f32 v[40:41], v[40:41], v[54:55]
	v_pk_add_f32 v[38:39], v[38:39], v[52:53]
	s_waitcnt vmcnt(0)
	v_pk_add_f32 v[44:45], v[36:37], v[58:59]
	v_pk_add_f32 v[42:43], v[34:35], v[56:57]
	v_mul_f32_e32 v34, v39, v39
	v_mul_f32_e32 v35, v41, v41
	v_mul_f32_e32 v36, v43, v43
	v_mul_f32_e32 v37, v45, v45
	v_fmac_f32_e32 v34, v38, v38
	v_fmac_f32_e32 v35, v40, v40
	v_fmac_f32_e32 v36, v42, v42
	v_fmac_f32_e32 v37, v44, v44
	v_add_f32_e32 v34, v34, v35
	v_add_f32_e32 v35, v36, v37
	v_add_f32_e32 v34, v35, v34
	v_add_f32_e32 v34, v46, v34
	ds_bpermute_b32 v35, v123, v34
	global_store_dwordx4 v[62:63], v[38:41], off offset:512
	global_store_dwordx4 v[62:63], v[42:45], off offset:528
	v_cvt_pk_bf16_f32 v36, v38, v39
	v_cvt_pk_bf16_f32 v37, v40, v41
	v_cvt_pk_bf16_f32 v38, v42, v43
	s_waitcnt lgkmcnt(0)
	v_add_f32_e32 v34, v34, v35
	ds_bpermute_b32 v35, v122, v34
	v_cvt_pk_bf16_f32 v39, v44, v45
	v_mov_b64_e32 v[180:181], v[36:37]
	v_mov_b64_e32 v[182:183], v[38:39]
	s_and_saveexec_b64 s[50:51], vcc
	s_cbranch_execz .LBB0_246
	v_readlane_b32 s28, v235, 1
	v_lshlrev_b64 v[36:37], 6, v[50:51]
	v_readlane_b32 s29, v235, 2
	s_lshl_b32 s78, s60, 2
	s_waitcnt lgkmcnt(0)
	v_add_f32_e32 v34, v34, v35
	v_lshl_add_u64 v[36:37], s[28:29], 0, v[36:37]
	v_lshl_add_u64 v[36:37], s[54:55], 2, v[36:37]
	v_lshl_add_u64 v[36:37], v[36:37], 0, s[78:79]
	s_mov_b32 s78, s76
	global_store_dword v[36:37], v34, off
.LBB0_246:
	s_or_b64 exec, exec, s[50:51]
	v_add_u32_e32 v34, 0xa0, v142
	s_waitcnt lgkmcnt(0)
	v_ashrrev_i32_e32 v35, 31, v34
	v_lshlrev_b64 v[36:37], 10, v[34:35]
	v_lshl_add_u64 v[44:45], v[36:37], 0, v[140:141]
	v_readlane_b32 s28, v235, 13
	v_lshlrev_b64 v[46:47], 2, v[44:45]
	v_readlane_b32 s29, v235, 14
	v_lshl_add_u64 v[44:45], v[44:45], 1, s[22:23]
	s_nop 0
	v_lshl_add_u64 v[48:49], s[28:29], 0, v[46:47]
	global_load_dwordx4 v[36:39], v[48:49], off
	global_load_dwordx4 v[40:43], v[48:49], off offset:16
	v_lshl_add_u64 v[46:47], s[70:71], 0, v[46:47]
	s_waitcnt vmcnt(1)
	v_pk_add_f32 v[32:33], v[32:33], v[38:39]
	v_pk_add_f32 v[30:31], v[30:31], v[36:37]
	s_waitcnt vmcnt(0)
	v_pk_add_f32 v[28:29], v[28:29], v[42:43]
	v_pk_add_f32 v[26:27], v[26:27], v[40:41]
	v_cvt_pk_bf16_f32 v36, v30, v31
	v_cvt_pk_bf16_f32 v37, v32, v33
	v_cvt_pk_bf16_f32 v38, v26, v27
	v_cvt_pk_bf16_f32 v39, v28, v29
	global_store_dwordx4 v[46:47], v[30:33], off
	global_store_dwordx4 v[46:47], v[26:29], off offset:16
	v_mov_b64_e32 v[184:185], v[36:37]
	v_mov_b64_e32 v[186:187], v[38:39]
	v_subrev_u32_e32 v253, s22, v44
	global_load_dwordx4 v[36:39], v[48:49], off offset:512
	s_nop 0
	global_load_dwordx4 v[40:43], v[48:49], off offset:528
	v_mul_f32_e32 v31, v31, v31
	v_mul_f32_e32 v33, v33, v33
	v_mul_f32_e32 v27, v27, v27
	v_mul_f32_e32 v29, v29, v29
	v_fmac_f32_e32 v31, v30, v30
	v_fmac_f32_e32 v33, v32, v32
	v_fmac_f32_e32 v27, v26, v26
	v_fmac_f32_e32 v29, v28, v28
	v_add_f32_e32 v26, v31, v33
	v_add_f32_e32 v27, v27, v29
	v_add_f32_e32 v30, v27, v26
	s_waitcnt vmcnt(1)
	v_pk_add_f32 v[24:25], v[24:25], v[38:39]
	v_pk_add_f32 v[22:23], v[22:23], v[36:37]
	s_waitcnt vmcnt(0)
	v_pk_add_f32 v[28:29], v[20:21], v[42:43]
	v_pk_add_f32 v[26:27], v[18:19], v[40:41]
	v_mul_f32_e32 v18, v23, v23
	v_mul_f32_e32 v19, v25, v25
	v_mul_f32_e32 v20, v27, v27
	v_mul_f32_e32 v21, v29, v29
	v_fmac_f32_e32 v18, v22, v22
	v_fmac_f32_e32 v19, v24, v24
	v_fmac_f32_e32 v20, v26, v26
	v_fmac_f32_e32 v21, v28, v28
	v_add_f32_e32 v18, v18, v19
	v_add_f32_e32 v19, v20, v21
	v_add_f32_e32 v18, v19, v18
	v_add_f32_e32 v18, v30, v18
	ds_bpermute_b32 v19, v123, v18
	global_store_dwordx4 v[46:47], v[22:25], off offset:512
	global_store_dwordx4 v[46:47], v[26:29], off offset:528
	v_cvt_pk_bf16_f32 v20, v22, v23
	v_cvt_pk_bf16_f32 v21, v24, v25
	v_cvt_pk_bf16_f32 v22, v26, v27
	s_waitcnt lgkmcnt(0)
	v_add_f32_e32 v18, v18, v19
	ds_bpermute_b32 v19, v122, v18
	v_cvt_pk_bf16_f32 v23, v28, v29
	v_mov_b64_e32 v[240:241], v[20:21]
	v_mov_b64_e32 v[242:243], v[22:23]
	s_and_saveexec_b64 s[50:51], vcc
	s_cbranch_execz .LBB0_248
	v_readlane_b32 s28, v235, 1
	v_lshlrev_b64 v[20:21], 6, v[34:35]
	v_readlane_b32 s29, v235, 2
	s_lshl_b32 s78, s60, 2
	s_waitcnt lgkmcnt(0)
	v_add_f32_e32 v18, v18, v19
	v_lshl_add_u64 v[20:21], s[28:29], 0, v[20:21]
	v_lshl_add_u64 v[20:21], s[54:55], 2, v[20:21]
	v_lshl_add_u64 v[20:21], v[20:21], 0, s[78:79]
	s_mov_b32 s78, s76
	global_store_dword v[20:21], v18, off
.LBB0_248:
	s_or_b64 exec, exec, s[50:51]
	v_add_u32_e32 v18, 0xb0, v142
	s_waitcnt lgkmcnt(0)
	v_ashrrev_i32_e32 v19, 31, v18
	v_lshlrev_b64 v[20:21], 10, v[18:19]
	v_lshl_add_u64 v[28:29], v[20:21], 0, v[140:141]
	v_readlane_b32 s28, v235, 13
	v_lshlrev_b64 v[30:31], 2, v[28:29]
	v_readlane_b32 s29, v235, 14
	v_lshl_add_u64 v[28:29], v[28:29], 1, s[22:23]
	s_nop 0
	v_lshl_add_u64 v[32:33], s[28:29], 0, v[30:31]
	global_load_dwordx4 v[20:23], v[32:33], off
	global_load_dwordx4 v[24:27], v[32:33], off offset:16
	v_lshl_add_u64 v[30:31], s[70:71], 0, v[30:31]
	s_waitcnt vmcnt(1)
	v_pk_add_f32 v[16:17], v[16:17], v[22:23]
	v_pk_add_f32 v[14:15], v[14:15], v[20:21]
	s_waitcnt vmcnt(0)
	v_pk_add_f32 v[12:13], v[12:13], v[26:27]
	v_pk_add_f32 v[10:11], v[10:11], v[24:25]
	v_cvt_pk_bf16_f32 v20, v14, v15
	v_cvt_pk_bf16_f32 v21, v16, v17
	v_cvt_pk_bf16_f32 v22, v10, v11
	v_cvt_pk_bf16_f32 v23, v12, v13
	global_store_dwordx4 v[30:31], v[14:17], off
	global_store_dwordx4 v[30:31], v[10:13], off offset:16
	v_mov_b64_e32 v[244:245], v[20:21]
	v_mov_b64_e32 v[246:247], v[22:23]
	v_subrev_u32_e32 v254, s22, v28
	global_load_dwordx4 v[20:23], v[32:33], off offset:512
	s_nop 0
	global_load_dwordx4 v[24:27], v[32:33], off offset:528
	v_mul_f32_e32 v15, v15, v15
	v_mul_f32_e32 v17, v17, v17
	v_mul_f32_e32 v11, v11, v11
	v_mul_f32_e32 v13, v13, v13
	v_fmac_f32_e32 v15, v14, v14
	v_fmac_f32_e32 v17, v16, v16
	v_fmac_f32_e32 v11, v10, v10
	v_fmac_f32_e32 v13, v12, v12
	v_add_f32_e32 v10, v15, v17
	v_add_f32_e32 v11, v11, v13
	v_add_f32_e32 v14, v11, v10
	s_waitcnt vmcnt(1)
	v_pk_add_f32 v[8:9], v[8:9], v[22:23]
	v_pk_add_f32 v[6:7], v[6:7], v[20:21]
	s_waitcnt vmcnt(0)
	v_pk_add_f32 v[12:13], v[4:5], v[26:27]
	v_pk_add_f32 v[10:11], v[2:3], v[24:25]
	v_mul_f32_e32 v2, v7, v7
	v_mul_f32_e32 v3, v9, v9
	v_mul_f32_e32 v4, v11, v11
	v_mul_f32_e32 v5, v13, v13
	v_fmac_f32_e32 v2, v6, v6
	v_fmac_f32_e32 v3, v8, v8
	v_fmac_f32_e32 v4, v10, v10
	v_fmac_f32_e32 v5, v12, v12
	v_add_f32_e32 v2, v2, v3
	v_add_f32_e32 v3, v4, v5
	v_add_f32_e32 v2, v3, v2
	v_add_f32_e32 v2, v14, v2
	ds_bpermute_b32 v3, v123, v2
	global_store_dwordx4 v[30:31], v[6:9], off offset:512
	global_store_dwordx4 v[30:31], v[10:13], off offset:528
	v_cvt_pk_bf16_f32 v4, v6, v7
	v_cvt_pk_bf16_f32 v5, v8, v9
	v_cvt_pk_bf16_f32 v6, v10, v11
	s_waitcnt lgkmcnt(0)
	v_add_f32_e32 v2, v2, v3
	ds_bpermute_b32 v3, v122, v2
	v_cvt_pk_bf16_f32 v7, v12, v13
	v_mov_b64_e32 v[248:249], v[4:5]
	v_mov_b64_e32 v[250:251], v[6:7]
	s_and_saveexec_b64 s[50:51], vcc
	s_cbranch_execz .LBB0_250
	v_readlane_b32 s28, v235, 1
	v_lshlrev_b64 v[4:5], 6, v[18:19]
	v_readlane_b32 s29, v235, 2
	s_lshl_b32 s78, s60, 2
	s_waitcnt lgkmcnt(0)
	v_add_f32_e32 v2, v2, v3
	v_lshl_add_u64 v[4:5], s[28:29], 0, v[4:5]
	v_lshl_add_u64 v[4:5], s[54:55], 2, v[4:5]
	v_lshl_add_u64 v[4:5], v[4:5], 0, s[78:79]
	s_mov_b32 s78, s76
	global_store_dword v[4:5], v2, off
.LBB0_250:
	s_or_b64 exec, exec, s[50:51]
	global_store_dwordx4 v188, v[200:203], s[22:23]
	global_store_dwordx4 v188, v[204:207], s[22:23] offset:256
	global_store_dwordx4 v189, v[208:211], s[22:23]
	global_store_dwordx4 v189, v[212:215], s[22:23] offset:256
	global_store_dwordx4 v167, v[216:219], s[22:23]
	global_store_dwordx4 v167, v[220:223], s[22:23] offset:256
	global_store_dwordx4 v238, v[224:227], s[22:23]
	global_store_dwordx4 v238, v[228:231], s[22:23] offset:256
	global_store_dwordx4 v239, v[168:171], s[22:23]
	global_store_dwordx4 v239, v[172:175], s[22:23] offset:256
	global_store_dwordx4 v252, v[176:179], s[22:23]
	global_store_dwordx4 v252, v[180:183], s[22:23] offset:256
	global_store_dwordx4 v253, v[184:187], s[22:23]
	global_store_dwordx4 v253, v[240:243], s[22:23] offset:256
	global_store_dwordx4 v254, v[244:247], s[22:23]
	global_store_dwordx4 v254, v[248:251], s[22:23] offset:256
	s_andn2_b64 vcc, exec, s[46:47]
	s_mov_b64 s[28:29], -1
	s_cbranch_vccnz .LBB0_225
	s_andn2_b64 vcc, exec, s[38:39]
	s_cbranch_vccnz .LBB0_224
	s_barrier
	s_branch .LBB0_224
